# adds SWA counted vmcnt wait: sink load hoisted before next-unit prefetch so the q wait no longer drains the prefetch
# baseline (speedup 1.0000x reference)
; __device__ __forceinline__ unsigned pk2(float lo, float hi) { return pg8::cvt_pk_bf16(lo, hi); }
; #define WG_BAR() __syncthreads()
; __device__ __forceinline__ void swa_phase(int first, int stride, const bf16* qkv, bf16* Y, const float* sinks, LAS unsigned char* lds) {
;     ...
;         const int head = 4 * kvh + (wave >> 1), qtok = 64 * tb + 32 * (wave & 1) + r32;
;         const size_t row = (size_t)b * SEQ + qtok;
; #pragma unroll
;         for (int i = 0; i < 3; ++i) if (i < nt) stage_st(st[i], lds + i * AL_KSZ, lds + SV0 + i * AL_VSZ, tid);
;         bf16x8 qf[4];
;         { const bf16* qp = qkv + row * PA + C_AQ + head * 64 + hi * 8;
; #pragma unroll
;           for (int d0 = 0; d0 < 4; ++d0) qf[d0] = *(const bf16x8*)(qp + 16 * d0); }
;         WG_BAR();
;         { const int un = u + stride;
;           if (un < 2048) { const int tb2 = un & 127, kvh2 = (un >> 7) & 1, b2 = un >> 8; const int nt2 = (tb2 + 1 < 3) ? tb2 + 1 : 3;
;             const bf16* Kg = qkv + (size_t)b2 * SEQ * PA + C_AK + kvh2 * 64; const bf16* Vg = qkv + (size_t)b2 * SEQ * PA + C_AV + kvh2 * 64;
; #pragma unroll
;             for (int i = 0; i < 3; ++i) if (i < nt2) stage_ld(st[i], Kg, Vg, 64 * (tb2 - i), tid); } }
;         const float sl2 = exp2f(-0.5f * (float)(head + 1)) * LOG2E;
;         float m = sinks[head] * LOG2E, l = (hi == 0) ? 1.f : 0.f;
;         f32x16 o0, o1;
; #pragma unroll
;         for (int r = 0; r < 16; ++r) { o0[r] = 0.f; o1[r] = 0.f; }
;         bf16x8 kx0, kx1, qx;
;         { const float xs = sl2 * (1.f / (0.125f * LOG2E)); const unsigned shb = pk2(xs, 0.f) & 0xffffu; const float res = xs - __uint_as_float(shb << 16);
.LBB0_391:
	s_ashr_i32 s0, s46, 8
	s_lshr_b32 s1, s46, 5
	s_and_b32 s3, s1, 4
	s_lshl_b32 s2, s34, 6
	s_ashr_i32 s1, s0, 31
	v_or_b32_e32 v2, s2, v123
	s_lshl_b64 s[0:1], s[0:1], 13
	v_add_u32_e32 v0, s3, v122
	v_or_b32_e32 v132, s0, v2
	v_mov_b64_e32 v[4:5], s[36:37]
	s_movk_i32 s0, 0x1e00
	v_mad_u64_u32 v[4:5], s[6:7], v132, s0, v[4:5]
	v_lshlrev_b32_e32 v120, 6, v0
	v_mad_i32_i24 v5, s1, v226, v5
	v_ashrrev_i32_e32 v121, 31, v120
	v_lshl_add_u64 v[4:5], v[120:121], 1, v[4:5]
	v_lshlrev_b32_e32 v64, 1, v116
	v_lshl_add_u64 v[4:5], v[4:5], 0, v[64:65]
	global_load_dwordx4 v[112:115], v[4:5], off
	global_load_dwordx4 v[108:111], v[4:5], off offset:32
	global_load_dwordx4 v[104:107], v[4:5], off offset:64
	global_load_dwordx4 v[100:103], v[4:5], off offset:96
	v_mov_b32_e32 v133, s1
	v_readlane_b32 s0, v253, 51
	s_add_i32 s46, s46, s0
	s_cmpk_gt_i32 s46, 0x7ff
	s_cselect_b64 s[54:55], -1, 0
	s_and_b64 vcc, exec, s[54:55]
	s_waitcnt lgkmcnt(0)
	s_barrier
	v_readlane_b32 s1, v253, 52
	v_ashrrev_i32_e32 v1, 31, v0
	v_lshl_add_u64 v[4:5], v[0:1], 2, s[38:39]
	global_load_dword v33, v[4:5], off
	s_mov_b32 s98, 0
	s_cbranch_vccnz .LBB0_396
	s_ashr_i32 s0, s46, 8
	s_and_b32 s3, s46, 0x7f
	s_mul_hi_i32 s1, s0, 0x3c00000
	s_mul_i32 s0, s0, 0x3c00000
	s_add_u32 s0, s36, s0
	s_addc_u32 s1, s37, s1
	s_and_b32 s6, s46, 0x80
	v_lshl_add_u32 v1, s3, 6, v117
	s_add_u32 s0, s0, s6
	v_mad_i64_i32 v[4:5], s[6:7], v1, s59, 0
	s_addc_u32 s1, s1, 0
	v_or_b32_e32 v4, v4, v119
	v_lshl_add_u64 v[4:5], v[4:5], 1, s[0:1]
	global_load_dwordx4 v[68:71], v[4:5], off offset:1024
	global_load_dwordx4 v[72:75], v[4:5], off offset:1280
	s_mov_b32 s98, 2
	s_cmp_eq_u32 s3, 0
	s_cbranch_scc1 .LBB0_394
	v_subrev_u32_e32 v3, 64, v1
	v_mad_i64_i32 v[4:5], s[6:7], v3, s59, 0
	v_or_b32_e32 v4, v4, v119
	v_lshl_add_u64 v[4:5], v[4:5], 1, s[0:1]
	global_load_dwordx4 v[76:79], v[4:5], off offset:1024
	global_load_dwordx4 v[80:83], v[4:5], off offset:1280
	s_mov_b32 s98, 4
.LBB0_394:
	s_cmp_lt_u32 s3, 2
	s_cbranch_scc1 .LBB0_396
	v_add_u32_e32 v1, 0xffffff80, v1
	v_mad_i64_i32 v[4:5], s[6:7], v1, s59, 0
	v_or_b32_e32 v4, v4, v119
	v_lshl_add_u64 v[4:5], v[4:5], 1, s[0:1]
	global_load_dwordx4 v[84:87], v[4:5], off offset:1024
	global_load_dwordx4 v[88:91], v[4:5], off offset:1280
	s_mov_b32 s98, 6
.LBB0_396:
	v_add_u32_e32 v0, 1, v0
	v_cvt_f32_i32_e32 v0, v0
	s_mov_b32 s0, 0xc2fc0000
	s_movk_i32 s13, 0xffc6
	s_movk_i32 s12, 0xffe6
	v_mul_f32_e32 v1, -0.5, v0
	v_cmp_gt_f32_e32 vcc, s0, v1
	v_mov_b32_e32 v64, 0
	s_nop 0
	v_cndmask_b32_e32 v1, 0, v227, vcc
	v_fmac_f32_e32 v1, -0.5, v0
	v_exp_f32_e32 v0, v1
	v_cndmask_b32_e32 v1, 0, v229, vcc
	v_ldexp_f32 v0, v0, v1
	v_mul_f32_e32 v134, 0x3fb8aa3b, v0
	s_and_saveexec_b64 s[0:1], s[4:5]
	v_mul_f32_e32 v0, 0x40b17218, v134
	v_cvt_pk_bf16_f32 v0, v0, 0
	v_and_b32_e32 v1, 0xffff, v0
	v_lshlrev_b32_e32 v0, 16, v0
	s_mov_b32 s3, 0x40b17218
	v_fma_f32 v0, v134, s3, -v0
	v_cvt_pk_bf16_f32 v0, v0, 0
	v_lshl_or_b32 v64, v0, 16, v1
	s_or_b64 exec, exec, s[0:1]
	v_mov_b32_e32 v66, v65
	v_mov_b32_e32 v67, v65
	v_sub_u32_e32 v48, s2, v2
	ds_read_b128 v[36:39], v129 offset:4608
	ds_read_b128 v[40:43], v129
	ds_read_b128 v[44:47], v129 offset:32
	v_mfma_f32_32x32x16_bf16 v[16:31], v[92:95], v[64:67], 0
	s_movk_i32 s0, 0xffdd
	v_cvt_f32_i32_e32 v32, v48
	s_cselect_b32 s99, 1, 0
	s_cmp_lt_u32 s98, 6
	s_cbranch_scc1 .Lmy_sw_4
	s_waitcnt vmcnt(6)
	s_branch .Lmy_sw_d
.Lmy_sw_4:
	s_cmp_lt_u32 s98, 4
	s_cbranch_scc1 .Lmy_sw_2
	s_waitcnt vmcnt(4)
	s_branch .Lmy_sw_d
.Lmy_sw_2:
	s_cmp_lt_u32 s98, 2
	s_cbranch_scc1 .Lmy_sw_0
	s_waitcnt vmcnt(2)
	s_branch .Lmy_sw_d

; #define LAS __attribute__((address_space(3)))
; template <int MASK> ...
;     ...
;     p0 = __builtin_amdgcn_mfma_f32_32x32x16_bf16(kx0, qx, p0, 0, 0, 0);
;     p1 = __builtin_amdgcn_mfma_f32_32x32x16_bf16(kx1, qx, p1, 0, 0, 0);
;     LAS const unsigned char* kp = Kb + r32 * 144 + hi * 16;
; #pragma unroll
;     for (int d0 = 0; d0 < 4; ++d0) {
;         const bf16x8 a0 = *(LAS const bf16x8*)(kp + d0 * 32), a1 = *(LAS const bf16x8*)(kp + 32 * 144 + d0 * 32);
;         p0 = __builtin_amdgcn_mfma_f32_32x32x16_bf16(a0, qf[d0], p0, 0, 0, 0);
;         p1 = __builtin_amdgcn_mfma_f32_32x32x16_bf16(a1, qf[d0], p1, 0, 0, 0);
;     }
;     constexpr float C2 = 0.125f * LOG2E;
;     const float NEG = -INFINITY;
;     if (MASK != 0) {
;         const int dk0 = kq + 4 * hi;
; #pragma unroll
;         for (int r = 0; r < 16; ++r) { const int kk = (r & 3) + 8 * (r >> 2);
;             if (MASK == 1) { if (dk0 > -kk) p0[r] = NEG; if (dk0 > -(kk + 32)) p1[r] = NEG; }
;             if (MASK == 3) { if (dk0 <= -128 - kk) p0[r] = NEG; if (dk0 <= -160 - kk) p1[r] = NEG; } }
;     }
;     float mr = fmaxf(p0[0], p1[0]);
; #pragma unroll
;     for (int r = 1; r < 16; ++r) mr = fmaxf(fmaxf(mr, p0[r]), p1[r]);
;     float mx = fmaf(mr, C2, off);
;     mx = fmaxf(mx, __shfl_xor(mx, 32));
.Lmy_sw_d:
	s_cmp_lg_u32 s99, 0
	v_mul_f32_e32 v34, 0x3fb8aa3b, v33
	v_mul_f32_e32 v35, v134, v32
	v_mfma_f32_32x32x16_bf16 v[0:15], v[96:99], v[64:67], 0
	s_waitcnt lgkmcnt(1)
	v_mfma_f32_32x32x16_bf16 v[16:31], v[40:43], v[112:115], v[16:31]
	v_mfma_f32_32x32x16_bf16 v[0:15], v[36:39], v[112:115], v[0:15]
	ds_read_b128 v[36:39], v129 offset:4640
	s_waitcnt lgkmcnt(1)
	v_mfma_f32_32x32x16_bf16 v[16:31], v[44:47], v[108:111], v[16:31]
	s_waitcnt lgkmcnt(0)
	v_mfma_f32_32x32x16_bf16 v[0:15], v[36:39], v[108:111], v[0:15]
	ds_read_b128 v[36:39], v129 offset:64
	ds_read_b128 v[40:43], v129 offset:4672
	s_waitcnt lgkmcnt(1)
	v_mfma_f32_32x32x16_bf16 v[16:31], v[36:39], v[104:107], v[16:31]
	s_waitcnt lgkmcnt(0)
	v_mfma_f32_32x32x16_bf16 v[0:15], v[40:43], v[104:107], v[0:15]
	ds_read_b128 v[36:39], v129 offset:96
	ds_read_b128 v[40:43], v129 offset:4704
	s_waitcnt lgkmcnt(1)
	v_mfma_f32_32x32x16_bf16 v[16:31], v[36:39], v[100:103], v[16:31]
	v_add_u32_e32 v38, v48, v118
	v_cmp_lt_i32_e64 s[76:77], s0, v38
	s_movk_i32 s0, 0xffd6
	v_cmp_lt_i32_e64 s[82:83], s0, v38
	s_movk_i32 s0, 0xffd5
	v_cmp_lt_i32_e64 s[84:85], s0, v38
	s_movk_i32 s0, 0xffd0
	v_cmp_lt_i32_e64 s[86:87], s0, v38
	s_movk_i32 s0, 0xffcf
	v_cmp_lt_i32_e64 s[22:23], s88, v38
	v_cmp_lt_i32_e64 s[88:89], s0, v38
	s_movk_i32 s0, 0xffce
	v_cmp_gt_i32_e32 vcc, 1, v38
	v_cmp_gt_i32_e64 s[6:7], 0, v38
	v_cmp_lt_i32_e64 s[24:25], s90, v38
	v_cmp_lt_i32_e64 s[90:91], s0, v38
	s_movk_i32 s0, 0xffed
	s_or_b64 vcc, s[6:7], vcc
	v_cmp_lt_i32_e64 s[26:27], s0, v38
	s_movk_i32 s0, 0xffcd
	v_cndmask_b32_e32 v37, v228, v16, vcc
	v_cndmask_b32_e64 v36, v228, v17, s[6:7]
	v_cmp_lt_i32_e64 s[92:93], s0, v38
	s_movk_i32 s0, 0xffc8
	s_movk_i32 s6, 0xffc7
	v_cmp_lt_i32_e32 vcc, s12, v38
	s_movk_i32 s12, 0xffe5
	v_cmp_lt_i32_e64 s[28:29], s94, v38
	v_cmp_lt_i32_e64 s[94:95], s0, v38
	v_cmp_lt_i32_e64 s[0:1], s96, v38
	v_cmp_lt_i32_e64 s[96:97], s6, v38
	v_cmp_lt_i32_e64 s[6:7], s13, v38
	v_cmp_lt_i32_e64 s[12:13], s12, v38
	s_and_b64 vcc, s[12:13], vcc
	s_and_b64 s[0:1], vcc, s[0:1]
	s_and_b64 s[28:29], s[0:1], s[28:29]
	s_and_b64 s[26:27], s[28:29], s[26:27]
	s_and_b64 s[24:25], s[26:27], s[24:25]
	v_cmp_lt_i32_e64 s[20:21], -16, v38
	s_and_b64 s[22:23], s[24:25], s[22:23]
	v_cmp_lt_i32_e64 s[18:19], -11, v38
	s_and_b64 s[20:21], s[22:23], s[20:21]
	s_waitcnt lgkmcnt(0)
	v_mfma_f32_32x32x16_bf16 v[0:15], v[40:43], v[100:103], v[0:15]
	v_cmp_lt_i32_e64 s[16:17], -10, v38
	s_and_b64 s[18:19], s[20:21], s[18:19]
	v_cmp_lt_i32_e64 s[14:15], -9, v38
	s_and_b64 s[16:17], s[18:19], s[16:17]
	v_cmp_lt_i32_e64 s[10:11], -8, v38
	s_and_b64 s[14:15], s[16:17], s[14:15]
	v_cmp_lt_i32_e64 s[8:9], -3, v38
	s_and_b64 s[10:11], s[14:15], s[10:11]
	v_cmp_lt_i32_e64 s[2:3], -2, v38
	s_and_b64 s[8:9], s[10:11], s[8:9]
	s_and_b64 s[2:3], s[8:9], s[2:3]
	v_cndmask_b32_e64 v29, v29, v228, s[0:1]
	s_movk_i32 s0, 0xffc5
	v_cndmask_b32_e64 v36, v17, v36, s[2:3]
	v_cndmask_b32_e32 v17, v30, v228, vcc
	v_cmp_lt_i32_e32 vcc, s0, v38
	s_and_b64 s[0:1], vcc, s[6:7]
	v_cndmask_b32_e64 v30, v14, v228, s[0:1]
	s_and_b64 s[0:1], s[0:1], s[96:97]
	v_cndmask_b32_e64 v37, v16, v37, s[2:3]
	v_cndmask_b32_e64 v16, v31, v228, s[12:13]
	v_cndmask_b32_e64 v31, v13, v228, s[0:1]
	s_and_b64 s[0:1], s[0:1], s[94:95]
	v_cmp_lt_i32_e64 s[30:31], s75, v38
	v_cmp_lt_i32_e64 s[72:73], s72, v38
	v_cmp_lt_i32_e64 s[74:75], s74, v38
	v_cmp_lt_i32_e64 s[78:79], s78, v38
	v_cmp_lt_i32_e64 s[80:81], s80, v38
	v_cndmask_b32_e64 v38, v12, v228, s[0:1]
	s_and_b64 s[0:1], s[0:1], s[92:93]
	v_cndmask_b32_e64 v39, v11, v228, s[0:1]
	s_and_b64 s[0:1], s[0:1], s[90:91]
	v_cndmask_b32_e64 v40, v10, v228, s[0:1]
	s_and_b64 s[0:1], s[0:1], s[88:89]
	v_cndmask_b32_e64 v41, v9, v228, s[0:1]
	s_and_b64 s[0:1], s[0:1], s[86:87]
	v_cndmask_b32_e64 v42, v8, v228, s[0:1]
	s_and_b64 s[0:1], s[0:1], s[84:85]
	v_cndmask_b32_e64 v43, v7, v228, s[0:1]
	s_and_b64 s[0:1], s[0:1], s[82:83]
	v_cndmask_b32_e64 v44, v6, v228, s[0:1]
	s_and_b64 s[0:1], s[0:1], s[80:81]
	v_cndmask_b32_e64 v45, v5, v228, s[0:1]
	s_and_b64 s[0:1], s[0:1], s[78:79]
	v_cndmask_b32_e64 v46, v4, v228, s[0:1]
	s_and_b64 s[0:1], s[0:1], s[76:77]
	v_cndmask_b32_e64 v47, v3, v228, s[0:1]
	s_and_b64 s[0:1], s[0:1], s[74:75]
	v_cndmask_b32_e64 v48, v2, v228, s[0:1]
	s_and_b64 s[0:1], s[0:1], s[72:73]
	v_cndmask_b32_e64 v49, v1, v228, s[0:1]
	s_and_b64 s[0:1], s[0:1], s[30:31]
	v_cndmask_b32_e64 v50, v0, v228, s[0:1]
	v_max_f32_e32 v0, v37, v37
	v_max_f32_e32 v1, v50, v50
	v_max_f32_e32 v0, v0, v1
	v_cndmask_b32_e64 v18, v18, v228, s[2:3]
	v_max3_f32 v0, v0, v36, v49
	v_cndmask_b32_e64 v19, v19, v228, s[8:9]
	v_max3_f32 v0, v0, v18, v48
	v_cndmask_b32_e64 v20, v20, v228, s[10:11]
	v_max3_f32 v0, v0, v19, v47
	v_cndmask_b32_e64 v21, v21, v228, s[14:15]
	v_max3_f32 v0, v0, v20, v46
	v_cndmask_b32_e64 v22, v22, v228, s[16:17]
	v_max3_f32 v0, v0, v21, v45
	v_cndmask_b32_e64 v23, v23, v228, s[18:19]
	v_max3_f32 v0, v0, v22, v44
	v_cndmask_b32_e64 v24, v24, v228, s[20:21]
	v_max3_f32 v0, v0, v23, v43
	v_cndmask_b32_e64 v25, v25, v228, s[22:23]
	v_max3_f32 v0, v0, v24, v42
	v_cndmask_b32_e64 v26, v26, v228, s[24:25]
	v_max3_f32 v0, v0, v25, v41
	v_cndmask_b32_e64 v27, v27, v228, s[26:27]
	v_max3_f32 v0, v0, v26, v40
	v_cndmask_b32_e64 v28, v28, v228, s[28:29]
	v_max3_f32 v0, v0, v27, v39
	v_max3_f32 v0, v0, v28, v38
	v_max3_f32 v0, v0, v29, v31
	v_cndmask_b32_e32 v60, v15, v228, vcc
	v_max3_f32 v0, v0, v17, v30
	v_max3_f32 v0, v0, v16, v60
	v_fmac_f32_e32 v35, 0x3e38aa3b, v0
	ds_bpermute_b32 v0, v126, v35
	s_mov_b32 s2, 0x3fb8aa3b
	s_waitcnt lgkmcnt(0)
; #define LAS __attribute__((address_space(3)))
; __device__ __forceinline__ unsigned pk2(float lo, float hi) { return pg8::cvt_pk_bf16(lo, hi); }
; template <int MASK> ...
;     ...
;     const float mn = fmaxf(m, mx);
;     if (__ballot(mn > m) != 0ull) {
;         const float alpha = __builtin_amdgcn_exp2f(m - mn); l *= alpha;
; #pragma unroll
;         for (int r = 0; r < 16; ++r) { o0[r] *= alpha; o1[r] *= alpha; }
;     }
;     m = mn;
;     const float sh = off - mn;
;     float rs = 0.f;
; #pragma unroll
;     for (int r = 0; r < 16; ++r) { p0[r] = __builtin_amdgcn_exp2f(fmaf(p0[r], C2, sh)); p1[r] = __builtin_amdgcn_exp2f(fmaf(p1[r], C2, sh)); rs += p0[r] + p1[r]; }
;     l += rs;
;     u32x4 pw[4];
;     pw[0] = (u32x4){pk2(p0[0], p0[1]), pk2(p0[2], p0[3]), pk2(p0[4], p0[5]), pk2(p0[6], p0[7])};
;     pw[1] = (u32x4){pk2(p0[8], p0[9]), pk2(p0[10], p0[11]), pk2(p0[12], p0[13]), pk2(p0[14], p0[15])};
;     pw[2] = (u32x4){pk2(p1[0], p1[1]), pk2(p1[2], p1[3]), pk2(p1[4], p1[5]), pk2(p1[6], p1[7])};
;     pw[3] = (u32x4){pk2(p1[8], p1[9]), pk2(p1[10], p1[11]), pk2(p1[12], p1[13]), pk2(p1[14], p1[15])};
;     LAS const unsigned char* vp = Vb + r32 * 136 + hi * 8;
; #pragma unroll
;     for (int ks = 0; ks < 4; ++ks) {
;         const int koff = (32 * (ks >> 1) + 16 * (ks & 1)) * 2;
;         const s16x4 a0l = *(LAS const s16x4*)(vp + koff), a0h = *(LAS const s16x4*)(vp + koff + 16);
;         const s16x4 a1l = *(LAS const s16x4*)(vp + 32 * 136 + koff), a1h = *(LAS const s16x4*)(vp + 32 * 136 + koff + 16);
;         const bf16x8 A0 = (bf16x8){a0l[0], a0l[1], a0l[2], a0l[3], a0h[0], a0h[1], a0h[2], a0h[3]};
;         const bf16x8 A1 = (bf16x8){a1l[0], a1l[1], a1l[2], a1l[3], a1h[0], a1h[1], a1h[2], a1h[3]};
;         const bf16x8 P = __builtin_bit_cast(bf16x8, pw[ks]);
;         o0 = __builtin_amdgcn_mfma_f32_32x32x16_bf16(A0, P, o0, 0, 0, 0);
;         o1 = __builtin_amdgcn_mfma_f32_32x32x16_bf16(A1, P, o1, 0, 0, 0);
;     }
	v_max3_f32 v137, v34, v35, v0
	v_fma_f32 v62, v134, v32, -v137
	v_fmamk_f32 v32, v37, 0x3e38aa3b, v62
	v_exp_f32_e32 v63, v32
	v_fmamk_f32 v32, v50, 0x3e38aa3b, v62
	v_exp_f32_e32 v136, v32
	v_fmamk_f32 v32, v36, 0x3e38aa3b, v62
	v_cmp_gt_f32_e32 vcc, v137, v34
	v_exp_f32_e32 v34, v32
	v_fmamk_f32 v32, v49, 0x3e38aa3b, v62
	v_exp_f32_e32 v32, v32
	v_fma_f32 v0, v33, s2, -v137
	v_add_f32_e32 v33, v136, v63
	v_mov_b32_e32 v35, v65
	v_fmamk_f32 v18, v18, 0x3e38aa3b, v62
	v_add_f32_e32 v36, v32, v34
	v_add_f32_e32 v37, v33, v35
	v_exp_f32_e32 v33, v18
	v_fmamk_f32 v18, v48, 0x3e38aa3b, v62
	v_add_f32_e32 v37, v36, v37
	v_add_f32_e32 v36, v36, v36
	v_exp_f32_e32 v35, v18
	v_fmamk_f32 v18, v19, 0x3e38aa3b, v62
	v_exp_f32_e32 v36, v18
	v_fmamk_f32 v18, v47, 0x3e38aa3b, v62
	v_exp_f32_e32 v48, v18
	v_add_f32_e32 v49, v35, v33
	v_fmamk_f32 v17, v17, 0x3e38aa3b, v62
	v_fmamk_f32 v16, v16, 0x3e38aa3b, v62
	v_add_f32_e32 v18, v48, v36
	v_add_f32_e32 v19, v49, v37
	v_exp_f32_e32 v0, v0
	v_add_f32_e32 v19, v18, v19
	v_add_f32_e32 v18, v18, v18
	v_fmamk_f32 v18, v20, 0x3e38aa3b, v62
	v_exp_f32_e32 v37, v18
	v_fmamk_f32 v18, v46, 0x3e38aa3b, v62
	v_exp_f32_e32 v49, v18
	v_fmamk_f32 v18, v21, 0x3e38aa3b, v62
	v_fmamk_f32 v20, v45, 0x3e38aa3b, v62
	v_exp_f32_e32 v18, v18
	v_exp_f32_e32 v50, v20
	v_add_f32_e32 v51, v49, v37
	s_cmp_eq_u64 vcc, 0
	v_cvt_pk_bf16_f32 v46, v37, v18
	v_add_f32_e32 v20, v50, v18
	v_add_f32_e32 v21, v51, v19
	v_fmamk_f32 v19, v22, 0x3e38aa3b, v62
	v_add_f32_e32 v21, v20, v21
	v_add_f32_e32 v20, v20, v20
	v_fmamk_f32 v20, v44, 0x3e38aa3b, v62
	v_exp_f32_e32 v19, v19
	v_exp_f32_e32 v51, v20
	v_fmamk_f32 v20, v23, 0x3e38aa3b, v62
	v_fmamk_f32 v22, v43, 0x3e38aa3b, v62
	v_exp_f32_e32 v20, v20
	v_exp_f32_e32 v52, v22
	v_add_f32_e32 v53, v51, v19
	v_cvt_pk_bf16_f32 v37, v35, v48
	s_cselect_b64 s[0:1], -1, 0
	v_add_f32_e32 v22, v52, v20
	v_add_f32_e32 v23, v53, v21
	v_fmamk_f32 v21, v24, 0x3e38aa3b, v62
	v_add_f32_e32 v23, v22, v23
	v_add_f32_e32 v22, v22, v22
	v_fmamk_f32 v22, v42, 0x3e38aa3b, v62
	v_exp_f32_e32 v21, v21
	v_exp_f32_e32 v53, v22
	v_fmamk_f32 v22, v25, 0x3e38aa3b, v62
	v_fmamk_f32 v24, v41, 0x3e38aa3b, v62
	v_exp_f32_e32 v22, v22
	v_exp_f32_e32 v54, v24
	v_add_f32_e32 v55, v53, v21
	v_cndmask_b32_e64 v61, v0, 1.0, s[0:1]
	v_cvt_pk_bf16_f32 v44, v63, v34
	v_add_f32_e32 v24, v54, v22
	v_add_f32_e32 v25, v55, v23
	v_fmamk_f32 v23, v26, 0x3e38aa3b, v62
	v_add_f32_e32 v25, v24, v25
	v_add_f32_e32 v24, v24, v24
	v_fmamk_f32 v24, v40, 0x3e38aa3b, v62
	v_exp_f32_e32 v23, v23
	v_exp_f32_e32 v55, v24
	v_fmamk_f32 v24, v27, 0x3e38aa3b, v62
	v_fmamk_f32 v26, v39, 0x3e38aa3b, v62
	v_exp_f32_e32 v24, v24
	v_exp_f32_e32 v56, v26
	v_add_f32_e32 v57, v55, v23
	v_cvt_pk_bf16_f32 v39, v51, v52
	v_cvt_pk_bf16_f32 v45, v33, v36
	v_add_f32_e32 v26, v56, v24
	v_add_f32_e32 v27, v57, v25
	v_fmamk_f32 v25, v28, 0x3e38aa3b, v62
	v_add_f32_e32 v27, v26, v27
	v_add_f32_e32 v26, v26, v26
	v_fmamk_f32 v26, v38, 0x3e38aa3b, v62
	v_exp_f32_e32 v25, v25
	v_exp_f32_e32 v57, v26
	v_fmamk_f32 v26, v29, 0x3e38aa3b, v62
	v_fmamk_f32 v28, v31, 0x3e38aa3b, v62
	v_exp_f32_e32 v26, v26
	v_exp_f32_e32 v58, v28
	v_add_f32_e32 v59, v57, v25
	v_cvt_pk_bf16_f32 v38, v49, v50
	v_cvt_pk_bf16_f32 v36, v136, v32
	v_add_f32_e32 v28, v58, v26
	v_add_f32_e32 v29, v59, v27
	v_exp_f32_e32 v27, v17
	v_fmamk_f32 v17, v30, 0x3e38aa3b, v62
	v_add_f32_e32 v29, v28, v29
	v_add_f32_e32 v28, v28, v28
	v_exp_f32_e32 v59, v17
	v_fmac_f32_e32 v62, 0x3e38aa3b, v60
	v_exp_f32_e32 v28, v16
	v_exp_f32_e32 v16, v62
	v_add_u32_e32 v60, 0x7800, v130
	ds_read2_b64 v[48:51], v60 offset0:160 offset1:162
	v_add_f32_e32 v17, v59, v27
	v_add_f32_e32 v30, v16, v28
	v_add_f32_e32 v31, v17, v29
	v_cvt_pk_bf16_f32 v32, v53, v54
	v_add_f32_e32 v135, v30, v31
	v_fmac_f32_e32 v135, v125, v61
	v_add_u32_e32 v61, 0x6800, v130
	v_cvt_pk_bf16_f32 v33, v55, v56
	v_cvt_pk_bf16_f32 v34, v57, v58
	v_cvt_pk_bf16_f32 v35, v59, v16
	ds_read2_b64 v[52:55], v61 offset0:128 offset1:130
	ds_read2_b64 v[56:59], v61 offset0:132 offset1:134
	v_mul_f32_e32 v1, 0, v0
	v_cndmask_b32_e64 v0, v1, 0, s[0:1]
	v_mov_b32_e32 v1, v0
	v_mov_b32_e32 v2, v0
	v_mov_b32_e32 v3, v0
	v_mov_b32_e32 v4, v0
	v_mov_b32_e32 v5, v0
	v_mov_b32_e32 v6, v0
	v_mov_b32_e32 v7, v0
	v_mov_b32_e32 v8, v0
	v_mov_b32_e32 v9, v0
	v_mov_b32_e32 v10, v0
	v_mov_b32_e32 v11, v0
	v_mov_b32_e32 v12, v0
	v_mov_b32_e32 v13, v0
	v_mov_b32_e32 v14, v0
	v_mov_b32_e32 v15, v0
	v_cvt_pk_bf16_f32 v47, v19, v20
	v_cvt_pk_bf16_f32 v40, v21, v22
	v_cvt_pk_bf16_f32 v41, v23, v24
	v_cvt_pk_bf16_f32 v42, v25, v26
	v_cvt_pk_bf16_f32 v43, v27, v28
	s_waitcnt lgkmcnt(1)
	v_mfma_f32_32x32x16_bf16 v[16:31], v[52:55], v[44:47], v[0:15]
	s_andn2_b64 vcc, exec, s[44:45]
	v_mfma_f32_32x32x16_bf16 v[0:15], v[48:51], v[44:47], v[0:15]
	ds_read2_b64 v[44:47], v60 offset0:164 offset1:166
	s_waitcnt lgkmcnt(1)
	v_mfma_f32_32x32x16_bf16 v[16:31], v[56:59], v[40:43], v[16:31]
	s_waitcnt lgkmcnt(0)
	v_mfma_f32_32x32x16_bf16 v[0:15], v[44:47], v[40:43], v[0:15]
	ds_read2_b64 v[40:43], v61 offset0:136 offset1:138
	ds_read2_b64 v[44:47], v60 offset0:168 offset1:170
	s_waitcnt lgkmcnt(1)
	v_mfma_f32_32x32x16_bf16 v[16:31], v[40:43], v[36:39], v[16:31]
	s_waitcnt lgkmcnt(0)
	v_mfma_f32_32x32x16_bf16 v[0:15], v[44:47], v[36:39], v[0:15]
	ds_read2_b64 v[36:39], v61 offset0:140 offset1:142
	ds_read2_b64 v[40:43], v60 offset0:172 offset1:174
	s_waitcnt lgkmcnt(1)
	v_mfma_f32_32x32x16_bf16 v[16:31], v[36:39], v[32:35], v[16:31]
	s_waitcnt lgkmcnt(0)
	v_mfma_f32_32x32x16_bf16 v[0:15], v[40:43], v[32:35], v[0:15]
	s_cbranch_vccnz .LBB0_402
; #define LAS __attribute__((address_space(3)))
; template <int MASK> ...
;     ...
;     for (int d0 = 0; d0 < 4; ++d0) {
;         const bf16x8 a0 = *(LAS const bf16x8*)(kp + d0 * 32), a1 = *(LAS const bf16x8*)(kp + 32 * 144 + d0 * 32);
;         p0 = __builtin_amdgcn_mfma_f32_32x32x16_bf16(a0, qf[d0], p0, 0, 0, 0);
;         p1 = __builtin_amdgcn_mfma_f32_32x32x16_bf16(a1, qf[d0], p1, 0, 0, 0);
;     }
;     constexpr float C2 = 0.125f * LOG2E;
;     const float NEG = -INFINITY;
;     if (MASK != 0) {
;         const int dk0 = kq + 4 * hi;
; #pragma unroll
;         for (int r = 0; r < 16; ++r) { const int kk = (r & 3) + 8 * (r >> 2);
;             if (MASK == 1) { if (dk0 > -kk) p0[r] = NEG; if (dk0 > -(kk + 32)) p1[r] = NEG; }
;             if (MASK == 3) { if (dk0 <= -128 - kk) p0[r] = NEG; if (dk0 <= -160 - kk) p1[r] = NEG; } }
;     }
;     float mr = fmaxf(p0[0], p1[0]);
; #pragma unroll
;     for (int r = 1; r < 16; ++r) mr = fmaxf(fmaxf(mr, p0[r]), p1[r]);
;     float mx = fmaf(mr, C2, off);
;     mx = fmaxf(mx, __shfl_xor(mx, 32));
;     const float mn = fmaxf(m, mx);
;     if (__ballot(mn > m) != 0ull) {
;         const float alpha = __builtin_amdgcn_exp2f(m - mn); l *= alpha;
; #pragma unroll
;         for (int r = 0; r < 16; ++r) { o0[r] *= alpha; o1[r] *= alpha; }
;     }
;     m = mn;
	ds_read_b128 v[138:141], v129 offset:9216
	v_mfma_f32_32x32x16_bf16 v[48:63], v[92:95], v[64:67], 0
	s_waitcnt lgkmcnt(0)
	v_mfma_f32_32x32x16_bf16 v[48:63], v[138:141], v[112:115], v[48:63]
	ds_read_b128 v[138:141], v129 offset:13824
	v_mfma_f32_32x32x16_bf16 v[32:47], v[96:99], v[64:67], 0
	s_waitcnt lgkmcnt(0)
	v_mfma_f32_32x32x16_bf16 v[32:47], v[138:141], v[112:115], v[32:47]
	ds_read_b128 v[138:141], v129 offset:9248
	s_waitcnt lgkmcnt(0)
	v_mfma_f32_32x32x16_bf16 v[48:63], v[138:141], v[108:111], v[48:63]
	ds_read_b128 v[138:141], v129 offset:13856
	s_waitcnt lgkmcnt(0)
	v_mfma_f32_32x32x16_bf16 v[32:47], v[138:141], v[108:111], v[32:47]
	ds_read_b128 v[138:141], v129 offset:9280
	s_waitcnt lgkmcnt(0)
	v_mfma_f32_32x32x16_bf16 v[48:63], v[138:141], v[104:107], v[48:63]
	ds_read_b128 v[138:141], v129 offset:13888
	s_waitcnt lgkmcnt(0)
	v_mfma_f32_32x32x16_bf16 v[32:47], v[138:141], v[104:107], v[32:47]
	ds_read_b128 v[138:141], v129 offset:13920
	s_waitcnt lgkmcnt(0)
	v_mfma_f32_32x32x16_bf16 v[32:47], v[138:141], v[100:103], v[32:47]
	ds_read_b128 v[140:143], v129 offset:9312
	v_mul_f32_e32 v138, v134, v127
	s_waitcnt lgkmcnt(0)
	v_mfma_f32_32x32x16_bf16 v[48:63], v[140:143], v[100:103], v[48:63]
	s_nop 7
	v_max_f32_e32 v136, v32, v32
	s_nop 2
	v_max_f32_e32 v139, v48, v48
	v_max_f32_e32 v136, v139, v136
	v_max3_f32 v136, v136, v49, v33
	v_max3_f32 v136, v136, v50, v34
	v_max3_f32 v136, v136, v51, v35
	v_max3_f32 v136, v136, v52, v36
	v_max3_f32 v136, v136, v53, v37
	v_max3_f32 v136, v136, v54, v38
	v_max3_f32 v136, v136, v55, v39
	v_max3_f32 v136, v136, v56, v40
	v_max3_f32 v136, v136, v57, v41
	v_max3_f32 v136, v136, v58, v42
	v_max3_f32 v136, v136, v59, v43
	v_max3_f32 v136, v136, v60, v44
	v_max3_f32 v136, v136, v61, v45
	v_max3_f32 v136, v136, v62, v46
	v_max3_f32 v136, v136, v63, v47
	v_fmamk_f32 v136, v136, 0x3e38aa3b, v138
	ds_bpermute_b32 v139, v126, v136
	s_waitcnt lgkmcnt(0)
	v_max3_f32 v136, v137, v136, v139
	v_cmp_gt_f32_e32 vcc, v136, v137
	s_cbranch_vccz .LBB0_401
	v_sub_f32_e32 v137, v137, v136
	v_exp_f32_e32 v140, v137
	s_nop 0
	v_mul_f32_e32 v135, v135, v140
	v_mul_f32_e32 v30, v30, v140
	v_mul_f32_e32 v31, v31, v140
	v_mul_f32_e32 v28, v28, v140
	v_mul_f32_e32 v29, v29, v140
	v_mul_f32_e32 v26, v26, v140
	v_mul_f32_e32 v27, v27, v140
	v_mul_f32_e32 v24, v24, v140
	v_mul_f32_e32 v25, v25, v140
	v_mul_f32_e32 v22, v22, v140
	v_mul_f32_e32 v23, v23, v140
	v_mul_f32_e32 v20, v20, v140
	v_mul_f32_e32 v21, v21, v140
	v_mul_f32_e32 v18, v18, v140
	v_mul_f32_e32 v19, v19, v140
	v_mul_f32_e32 v16, v16, v140
	v_mul_f32_e32 v17, v17, v140
	v_mul_f32_e32 v14, v14, v140
	v_mul_f32_e32 v15, v15, v140
	v_mul_f32_e32 v12, v12, v140
	v_mul_f32_e32 v13, v13, v140
	v_mul_f32_e32 v10, v10, v140
	v_mul_f32_e32 v11, v11, v140
	v_mul_f32_e32 v8, v8, v140
	v_mul_f32_e32 v9, v9, v140
	v_mul_f32_e32 v6, v6, v140
	v_mul_f32_e32 v7, v7, v140
	v_mul_f32_e32 v4, v4, v140
	v_mul_f32_e32 v5, v5, v140
	v_mul_f32_e32 v2, v2, v140
	v_mul_f32_e32 v3, v3, v140
	v_mul_f32_e32 v0, v0, v140
	v_mul_f32_e32 v1, v1, v140

; #define LAS __attribute__((address_space(3)))
; __global__ void __launch_bounds__(NTHR, 2) fwd_kernel(Args a) {
;     extern __shared__ __attribute__((aligned(16))) unsigned char lds_raw[];
;     LAS unsigned char* lds = (LAS unsigned char*)lds_raw;
	.amdhsa_kernel _Z10fwd_kernel4Args
		.amdhsa_group_segment_fixed_size 0
		.amdhsa_private_segment_fixed_size 0
		.amdhsa_kernarg_size 400
		.amdhsa_user_sgpr_count 2
		.amdhsa_user_sgpr_dispatch_ptr 0
		.amdhsa_user_sgpr_queue_ptr 0
		.amdhsa_user_sgpr_kernarg_segment_ptr 1
		.amdhsa_user_sgpr_dispatch_id 0
		.amdhsa_user_sgpr_kernarg_preload_length 0
		.amdhsa_user_sgpr_kernarg_preload_offset 0
		.amdhsa_user_sgpr_private_segment_size 0
		.amdhsa_uses_dynamic_stack 0
		.amdhsa_enable_private_segment 0
		.amdhsa_system_sgpr_workgroup_id_x 1
		.amdhsa_system_sgpr_workgroup_id_y 0
		.amdhsa_system_sgpr_workgroup_id_z 0
		.amdhsa_system_sgpr_workgroup_info 0
		.amdhsa_system_vgpr_workitem_id 2
		.amdhsa_next_free_vgpr 256
		.amdhsa_next_free_sgpr 102
		.amdhsa_accum_offset 256
		.amdhsa_reserve_vcc 1
		.amdhsa_float_round_mode_32 0
		.amdhsa_float_round_mode_16_64 0
		.amdhsa_float_denorm_mode_32 3
		.amdhsa_float_denorm_mode_16_64 3
		.amdhsa_dx10_clamp 1
		.amdhsa_ieee_mode 1
		.amdhsa_fp16_overflow 0
		.amdhsa_tg_split 0
		.amdhsa_exception_fp_ieee_invalid_op 0
		.amdhsa_exception_fp_denorm_src 0
		.amdhsa_exception_fp_ieee_div_zero 0
		.amdhsa_exception_fp_ieee_overflow 0
		.amdhsa_exception_fp_ieee_underflow 0
		.amdhsa_exception_fp_ieee_inexact 0
		.amdhsa_exception_int_div_zero 0
	.end_amdhsa_kernel

; #define LAS __attribute__((address_space(3)))
; __global__ void __launch_bounds__(NTHR, 2) fwd_kernel(Args a) {
;     extern __shared__ __attribute__((aligned(16))) unsigned char lds_raw[];
;     LAS unsigned char* lds = (LAS unsigned char*)lds_raw;
amdhsa.kernels:
  - .agpr_count:     0
    .args:
      - .offset:         0
        .size:           144
        .value_kind:     by_value
      - .offset:         144
        .size:           4
        .value_kind:     hidden_block_count_x
      - .offset:         148
        .size:           4
        .value_kind:     hidden_block_count_y
      - .offset:         152
        .size:           4
        .value_kind:     hidden_block_count_z
      - .offset:         156
        .size:           2
        .value_kind:     hidden_group_size_x
      - .offset:         158
        .size:           2
        .value_kind:     hidden_group_size_y
      - .offset:         160
        .size:           2
        .value_kind:     hidden_group_size_z
      - .offset:         162
        .size:           2
        .value_kind:     hidden_remainder_x
      - .offset:         164
        .size:           2
        .value_kind:     hidden_remainder_y
      - .offset:         166
        .size:           2
        .value_kind:     hidden_remainder_z
      - .offset:         184
        .size:           8
        .value_kind:     hidden_global_offset_x
      - .offset:         192
        .size:           8
        .value_kind:     hidden_global_offset_y
      - .offset:         200
        .size:           8
        .value_kind:     hidden_global_offset_z
      - .offset:         208
        .size:           2
        .value_kind:     hidden_grid_dims
      - .offset:         232
        .size:           8
        .value_kind:     hidden_multigrid_sync_arg
      - .offset:         264
        .size:           4
        .value_kind:     hidden_dynamic_lds_size
    .group_segment_fixed_size: 0
    .kernarg_segment_align: 8
    .kernarg_segment_size: 400
    .language:       OpenCL C
    .language_version:
      - 2
      - 0
    .max_flat_workgroup_size: 512
    .name:           _Z10fwd_kernel4Args
    .private_segment_fixed_size: 0
    .sgpr_count:     108
    .sgpr_spill_count: 248
    .symbol:         _Z10fwd_kernel4Args.kd
    .uniform_work_group_size: 1
    .uses_dynamic_stack: false
    .vgpr_count:     256
    .vgpr_spill_count: 0
    .wavefront_size: 64
